# HGRN chain: one-byte-per-line L2 prefetch of the chunk after next (48 lanes per wave), issued a stage before the real prefetch
# baseline (speedup 1.0000x reference)
; #define LAS __attribute__((address_space(3)))
; __device__ __forceinline__ float frcp(float x) { return __builtin_amdgcn_rcpf(x); }
; #define HG_ISSUE(t0n) do { _Pragma("unroll") for (int i = 0; i < 16; ++i) { const int tk = (t0n) + (dir ? 63 - (i0 + i) : (i0 + i)); const bf16_t* pr = Pb + (size_t)tk * HGP + h * 128 + dcol; \
;         rq[i] = pr[0]; rf[i] = pr[1024 * (1 + dir)]; rv[i] = pr[3072]; } } while (0)
; __device__ __forceinline__ void hgrn_chain(LAS unsigned char* lds, int cid, bf16_t* P1, const float* hg_lb, bf16_t* Ob, int ldo, int ocbase, int ocdir) {
;     ...
;     for (int e = tid; e < 128 * HLD / 2; e += 512) ((LAS unsigned*)ST)[e] = 0u;
;     const int dcol = tid & 127, qtr = tid >> 7, i0 = qtr * 16;
;     const float lbv = frcp(1.0f + __expf(hg_lb[h * 128 + dcol] - hg_lb[1024 + h * 128 + dcol]));
;     f32x4 st[8];
; #pragma unroll
;     for (int i = 0; i < 8; ++i) st[i] = (f32x4){0.f, 0.f, 0.f, 0.f};
;     bf16_t* Pb = P1 + (size_t)b * SEQ * HGP;
;     __syncthreads();
;     unsigned short rq[16], rf[16], rv[16];
;     ...
;     HG_ISSUE((dir ? 63 : 0) * 64);
.LBB0_1713:
	v_add_u32_e32 v1, 0x200, v1
	v_cmp_lt_u32_e32 vcc, s38, v1
	ds_write_b32 v0, v43
	s_or_b64 s[34:35], vcc, s[34:35]
	v_add_u32_e32 v0, 0x800, v0
	s_andn2_b64 exec, exec, s[34:35]
	s_cbranch_execnz .LBB0_1713
	s_or_b64 exec, exec, s[34:35]
	s_lshl_b32 s30, s41, 6
	s_and_b32 s30, s30, 0x380
	v_or_b32_e32 v0, s30, v40
	v_lshlrev_b32_e32 v42, 2, v0
	v_lshl_add_u64 v[0:1], s[24:25], 0, v[42:43]
	v_add_co_u32_e32 v0, vcc, 0x1000, v0
	s_ashr_i32 s34, s41, 4
	s_nop 0
	v_addc_co_u32_e32 v1, vcc, 0, v1, vcc
	global_load_dword v38, v42, s[24:25]
	global_load_dword v39, v[0:1], off
	s_and_b32 s37, s41, 1
	s_ashr_i32 s35, s34, 31
	s_mul_i32 s25, s34, 0x2800000
	s_mul_hi_i32 s24, s34, 0x2800000
	s_add_u32 s42, s72, s25
	s_addc_u32 s43, s73, s24
	s_cmp_eq_u32 s37, 0
	s_cselect_b64 s[24:25], -1, 0
	s_lshl_b32 s36, s30, 1
	s_add_u32 s42, s42, s36
	s_addc_u32 s43, s43, 0
	v_lshlrev_b32_e32 v42, 1, v40
	v_cndmask_b32_e64 v0, v104, v41, s[24:25]
	v_lshl_add_u64 v[48:49], s[42:43], 0, v[42:43]
	v_mul_u32_u24_e32 v42, 0x2800, v0
	v_lshl_add_u64 v[0:1], v[48:49], 0, v[42:43]
	v_cndmask_b32_e64 v4, v106, v105, s[24:25]
	v_add_co_u32_e32 v2, vcc, s39, v0
	v_mul_u32_u24_e32 v42, 0x2800, v4
	s_nop 0
	v_addc_co_u32_e32 v3, vcc, 0, v1, vcc
	v_lshl_add_u64 v[4:5], v[48:49], 0, v[42:43]
	v_add_co_u32_e32 v6, vcc, s39, v4
	s_waitcnt lgkmcnt(0)
	s_barrier
	v_addc_co_u32_e32 v7, vcc, 0, v5, vcc
	global_load_ushort v45, v[2:3], off offset:2048
	global_load_ushort v47, v[6:7], off offset:2048
	v_cndmask_b32_e64 v2, v108, v107, s[24:25]
	v_mul_u32_u24_e32 v42, 0x2800, v2
	v_lshl_add_u64 v[2:3], v[48:49], 0, v[42:43]
	v_cndmask_b32_e64 v8, v110, v109, s[24:25]
	v_add_co_u32_e32 v6, vcc, s39, v2
	v_mul_u32_u24_e32 v42, 0x2800, v8
	s_nop 0
	v_addc_co_u32_e32 v7, vcc, 0, v3, vcc
	v_lshl_add_u64 v[8:9], v[48:49], 0, v[42:43]
	v_cndmask_b32_e64 v12, v112, v111, s[24:25]
	v_add_co_u32_e32 v10, vcc, s39, v8
	v_mul_u32_u24_e32 v42, 0x2800, v12
	s_nop 0
	v_addc_co_u32_e32 v11, vcc, 0, v9, vcc
	v_lshl_add_u64 v[12:13], v[48:49], 0, v[42:43]
	v_add_co_u32_e32 v14, vcc, s39, v12
	v_cndmask_b32_e64 v18, v118, v117, s[24:25]
	s_nop 0
	v_addc_co_u32_e32 v15, vcc, 0, v13, vcc
	global_load_ushort v50, v[6:7], off offset:2048
	global_load_ushort v51, v[10:11], off offset:2048
	global_load_ushort v52, v[14:15], off offset:2048
	v_cndmask_b32_e64 v6, v114, v113, s[24:25]
	v_mul_u32_u24_e32 v42, 0x2800, v6
	v_lshl_add_u64 v[6:7], v[48:49], 0, v[42:43]
	v_cndmask_b32_e64 v14, v116, v115, s[24:25]
	v_add_co_u32_e32 v10, vcc, s39, v6
	v_mul_u32_u24_e32 v42, 0x2800, v14
	s_nop 0
	v_addc_co_u32_e32 v11, vcc, 0, v7, vcc
	v_lshl_add_u64 v[14:15], v[48:49], 0, v[42:43]
	v_add_co_u32_e32 v16, vcc, s39, v14
	v_mul_u32_u24_e32 v42, 0x2800, v18
	s_nop 0
	v_addc_co_u32_e32 v17, vcc, 0, v15, vcc
	v_lshl_add_u64 v[18:19], v[48:49], 0, v[42:43]
	v_add_co_u32_e32 v20, vcc, s39, v18
	v_cndmask_b32_e64 v24, v126, v125, s[24:25]
	s_nop 0
	v_addc_co_u32_e32 v21, vcc, 0, v19, vcc
	global_load_ushort v53, v[10:11], off offset:2048
	global_load_ushort v54, v[16:17], off offset:2048
	global_load_ushort v55, v[20:21], off offset:2048
	v_cndmask_b32_e64 v10, v120, v119, s[24:25]
	v_mul_u32_u24_e32 v42, 0x2800, v10
	v_lshl_add_u64 v[10:11], v[48:49], 0, v[42:43]
	v_cndmask_b32_e64 v20, v122, v121, s[24:25]
	v_add_co_u32_e32 v16, vcc, s39, v10
	v_mul_u32_u24_e32 v42, 0x2800, v20
	s_nop 0
	v_addc_co_u32_e32 v17, vcc, 0, v11, vcc
	v_lshl_add_u64 v[20:21], v[48:49], 0, v[42:43]
	v_add_co_u32_e32 v22, vcc, s39, v20
	v_cndmask_b32_e64 v28, v128, v127, s[24:25]
	s_nop 0
	v_addc_co_u32_e32 v23, vcc, 0, v21, vcc
	global_load_ushort v56, v[16:17], off offset:2048
	global_load_ushort v57, v[22:23], off offset:2048
	v_cndmask_b32_e64 v16, v124, v123, s[24:25]
	v_mul_u32_u24_e32 v42, 0x2800, v16
	v_lshl_add_u64 v[16:17], v[48:49], 0, v[42:43]
	v_add_co_u32_e32 v22, vcc, s39, v16
	v_mul_u32_u24_e32 v42, 0x2800, v24
	s_nop 0
	v_addc_co_u32_e32 v23, vcc, 0, v17, vcc
	v_lshl_add_u64 v[24:25], v[48:49], 0, v[42:43]
	v_add_co_u32_e32 v26, vcc, s39, v24
	v_mul_u32_u24_e32 v42, 0x2800, v28
	s_nop 0
	v_addc_co_u32_e32 v27, vcc, 0, v25, vcc
	v_lshl_add_u64 v[28:29], v[48:49], 0, v[42:43]
	v_add_co_u32_e32 v30, vcc, s39, v28
	v_cndmask_b32_e64 v34, v134, v133, s[24:25]
	s_nop 0
	v_addc_co_u32_e32 v31, vcc, 0, v29, vcc
	global_load_ushort v58, v[22:23], off offset:2048
	global_load_ushort v59, v[26:27], off offset:2048
	global_load_ushort v60, v[30:31], off offset:2048
	v_cndmask_b32_e64 v22, v130, v129, s[24:25]
	v_mul_u32_u24_e32 v42, 0x2800, v22
	v_lshl_add_u64 v[22:23], v[48:49], 0, v[42:43]
	v_cndmask_b32_e64 v30, v132, v131, s[24:25]
	v_add_co_u32_e32 v26, vcc, s39, v22
	v_mul_u32_u24_e32 v42, 0x2800, v30
	s_nop 0
	v_addc_co_u32_e32 v27, vcc, 0, v23, vcc
	v_lshl_add_u64 v[30:31], v[48:49], 0, v[42:43]
	v_add_co_u32_e32 v32, vcc, s39, v30
	v_mul_u32_u24_e32 v42, 0x2800, v34
	s_nop 0
	v_addc_co_u32_e32 v33, vcc, 0, v31, vcc
	v_lshl_add_u64 v[34:35], v[48:49], 0, v[42:43]
	v_add_co_u32_e32 v36, vcc, s39, v34
	s_lshl_b32 s30, s37, 11
	s_nop 0
	v_addc_co_u32_e32 v37, vcc, 0, v35, vcc
	global_load_ushort v42, v[26:27], off offset:2048
	global_load_ushort v61, v[32:33], off offset:2048
	global_load_ushort v62, v[36:37], off offset:2048
	v_lshl_add_u64 v[26:27], v[6:7], 0, s[30:31]
	v_lshl_add_u64 v[32:33], v[14:15], 0, s[30:31]
	v_lshl_add_u64 v[36:37], v[18:19], 0, s[30:31]
	global_load_ushort v207, v[26:27], off offset:2048
	global_load_ushort v209, v[14:15], off
	global_load_ushort v210, v[32:33], off offset:2048
	global_load_ushort v211, v[18:19], off
	global_load_ushort v212, v[36:37], off offset:2048
	v_lshl_add_u64 v[14:15], v[22:23], 0, s[30:31]
	v_lshl_add_u64 v[18:19], v[30:31], 0, s[30:31]
	v_lshl_add_u64 v[26:27], v[34:35], 0, s[30:31]
	global_load_ushort v219, v[14:15], off offset:2048
	global_load_ushort v220, v[30:31], off
	global_load_ushort v221, v[18:19], off offset:2048
	global_load_ushort v222, v[34:35], off
	global_load_ushort v223, v[26:27], off offset:2048
	s_waitcnt vmcnt(26)
; __device__ __forceinline__ float frcp(float x) { return __builtin_amdgcn_rcpf(x); }
; #define HG_ISSUE(t0n) do { _Pragma("unroll") for (int i = 0; i < 16; ++i) { const int tk = (t0n) + (dir ? 63 - (i0 + i) : (i0 + i)); const bf16_t* pr = Pb + (size_t)tk * HGP + h * 128 + dcol; \
;         rq[i] = pr[0]; rf[i] = pr[1024 * (1 + dir)]; rv[i] = pr[3072]; } } while (0)
; __device__ __forceinline__ void hgrn_chain(LAS unsigned char* lds, int cid, bf16_t* P1, const float* hg_lb, bf16_t* Ob, int ldo, int ocbase, int ocdir) {
;     ...
;     const int dcol = tid & 127, qtr = tid >> 7, i0 = qtr * 16;
;     const float lbv = frcp(1.0f + __expf(hg_lb[h * 128 + dcol] - hg_lb[1024 + h * 128 + dcol]));
;     f32x4 st[8];
; #pragma unroll
;     for (int i = 0; i < 8; ++i) st[i] = (f32x4){0.f, 0.f, 0.f, 0.f};
;     bf16_t* Pb = P1 + (size_t)b * SEQ * HGP;
;     __syncthreads();
;     unsigned short rq[16], rf[16], rv[16];
;     ...
;     HG_ISSUE((dir ? 63 : 0) * 64);
	v_sub_f32_e32 v14, v38, v39
	v_mul_f32_e32 v30, 0x3fb8aa3b, v14
	v_lshl_add_u64 v[14:15], v[0:1], 0, s[30:31]
	v_lshl_add_u64 v[18:19], v[4:5], 0, s[30:31]
	v_lshl_add_u64 v[26:27], v[2:3], 0, s[30:31]
	global_load_ushort v179, v[0:1], off
	global_load_ushort v180, v[14:15], off offset:2048
	global_load_ushort v181, v[4:5], off
	global_load_ushort v182, v[18:19], off offset:2048
	global_load_ushort v183, v[2:3], off
	global_load_ushort v185, v[26:27], off offset:2048
	v_lshl_add_u64 v[0:1], v[8:9], 0, s[30:31]
	v_lshl_add_u64 v[2:3], v[12:13], 0, s[30:31]
	global_load_ushort v203, v[8:9], off
	global_load_ushort v204, v[0:1], off offset:2048
	global_load_ushort v205, v[12:13], off
	global_load_ushort v206, v[2:3], off offset:2048
	global_load_ushort v208, v[6:7], off
	v_lshl_add_u64 v[0:1], v[10:11], 0, s[30:31]
	v_lshl_add_u64 v[2:3], v[20:21], 0, s[30:31]
	v_lshl_add_u64 v[4:5], v[16:17], 0, s[30:31]
	global_load_ushort v213, v[10:11], off
	global_load_ushort v214, v[0:1], off offset:2048
	global_load_ushort v215, v[20:21], off
	global_load_ushort v216, v[2:3], off offset:2048
	global_load_ushort v217, v[16:17], off
	global_load_ushort v218, v[4:5], off offset:2048
	v_lshl_add_u64 v[0:1], v[24:25], 0, s[30:31]
	v_lshl_add_u64 v[2:3], v[28:29], 0, s[30:31]
	global_load_ushort v224, v[24:25], off
	global_load_ushort v225, v[0:1], off offset:2048
	global_load_ushort v226, v[28:29], off
	global_load_ushort v227, v[2:3], off offset:2048
	global_load_ushort v228, v[22:23], off
	v_exp_f32_e32 v0, v30
	s_lshl_b32 s44, s37, 10
	s_lshl_b64 s[34:35], s[34:35], 12
	s_add_u32 s30, s72, s30
	v_add_f32_e32 v0, 1.0, v0
	s_waitcnt vmcnt(44)
	v_lshl_or_b32 v33, v51, 16, v50
	v_rcp_f32_e32 v50, v0
	s_addc_u32 s37, s73, 0
	s_add_u32 s36, s30, s36
	v_lshl_or_b32 v32, v47, 16, v45
	s_addc_u32 s37, s37, 0
	v_mov_b32_e32 v45, v43
	v_lshl_add_u64 v[0:1], s[36:37], 0, v[44:45]
	v_mov_b32_e32 v47, v43
	s_waitcnt vmcnt(42)
	v_lshl_or_b32 v34, v53, 16, v52
	s_waitcnt vmcnt(40)
	v_lshl_or_b32 v35, v55, 16, v54
	v_sub_f32_e32 v52, 1.0, v50
	v_lshl_add_u64 v[54:55], v[0:1], 0, v[46:47]
	v_mov_b32_e32 v0, 0
	s_mov_b32 s42, 1
	s_waitcnt vmcnt(38)
	v_lshl_or_b32 v36, v57, 16, v56
	v_cndmask_b32_e64 v184, v142, v140, s[24:25]
	v_cndmask_b32_e64 v186, v145, v41, s[24:25]
	v_cndmask_b32_e64 v187, v146, v105, s[24:25]
	v_cndmask_b32_e64 v188, v147, v107, s[24:25]
	v_cndmask_b32_e64 v189, v148, v109, s[24:25]
	v_cndmask_b32_e64 v190, v149, v111, s[24:25]
	v_cndmask_b32_e64 v191, v150, v113, s[24:25]
	v_cndmask_b32_e64 v192, v151, v115, s[24:25]
	v_cndmask_b32_e64 v193, v152, v117, s[24:25]
	v_cndmask_b32_e64 v194, v153, v119, s[24:25]
	v_cndmask_b32_e64 v195, v154, v121, s[24:25]
	s_waitcnt vmcnt(36)
	v_lshl_or_b32 v37, v59, 16, v58
	v_cndmask_b32_e64 v196, v155, v123, s[24:25]
	v_cndmask_b32_e64 v197, v156, v125, s[24:25]
	v_cndmask_b32_e64 v198, v157, v127, s[24:25]
	v_cndmask_b32_e64 v199, v158, v129, s[24:25]
	v_cndmask_b32_e64 v201, v159, v131, s[24:25]
	v_cndmask_b32_e64 v202, v160, v133, s[24:25]
	v_mov_b32_e32 v51, v50
	v_mov_b32_e32 v53, v52
	s_mov_b32 s43, 62
	s_lshl_b32 s30, s44, 1
	v_mov_b32_e32 v1, v0
	v_mov_b32_e32 v2, v0
	v_mov_b32_e32 v3, v0
	v_mov_b32_e32 v4, v0
	v_mov_b32_e32 v5, v0
	v_mov_b32_e32 v6, v0
	v_mov_b32_e32 v7, v0
	v_mov_b32_e32 v8, v0
	v_mov_b32_e32 v9, v0
	v_mov_b32_e32 v10, v0
	s_waitcnt vmcnt(34)
	v_lshl_or_b32 v38, v42, 16, v60
	v_mov_b32_e32 v11, v0
	s_waitcnt vmcnt(32)
	v_lshl_or_b32 v39, v62, 16, v61
	v_mov_b32_e32 v16, v0
	v_mov_b32_e32 v17, v0
	v_mov_b32_e32 v18, v0
	v_mov_b32_e32 v19, v0
	v_mov_b32_e32 v12, v0
	v_mov_b32_e32 v13, v0
	v_mov_b32_e32 v14, v0
	v_mov_b32_e32 v15, v0
	v_mov_b32_e32 v24, v0
	v_mov_b32_e32 v25, v0
	v_mov_b32_e32 v26, v0
	v_mov_b32_e32 v27, v0
	v_mov_b32_e32 v20, v0
	v_mov_b32_e32 v21, v0
	v_mov_b32_e32 v22, v0
	v_mov_b32_e32 v23, v0
	v_mov_b32_e32 v28, v0
	v_mov_b32_e32 v29, v0
	v_mov_b32_e32 v30, v0
	v_mov_b32_e32 v31, v0
	s_waitcnt vmcnt(0)
	s_branch .LBB0_1716

; #define LAS __attribute__((address_space(3)))
; __device__ __forceinline__ float sigmoidf_(float x) { return frcp(1.0f + __expf(-x)); }
; __device__ __forceinline__ void hgrn_chain(LAS unsigned char* lds, int cid, bf16_t* P1, const float* hg_lb, bf16_t* Ob, int ldo, int ocbase, int ocdir) {
;     ...
;     for (int cc = 0; cc < 64; ++cc) {
;         const int t0 = (dir ? 63 - cc : cc) * 64;
;         float gq[16], gk[16], gc[16]; float run = 1.0f;
; #pragma unroll
;         for (int i = 0; i < 16; ++i) { const float q = bf2f(rq[i]), fr_ = bf2f(rf[i]);
;             const float f = lbv + (1.0f - lbv) * sigmoidf_(fr_); run *= f; gq[i] = q; gk[i] = 1.0f - f; gc[i] = run; }
;         totS[qtr * 128 + dcol] = run;
; #pragma unroll
;         for (int i = 0; i < 16; i += 2) *(LAS unsigned*)(VT + dcol * HLS + i0 + i) = (unsigned)rv[i] | ((unsigned)rv[i + 1] << 16);
;         __syncthreads();
.LBB0_1716:
	s_waitcnt vmcnt(20)
	v_lshlrev_b32_e32 v42, 16, v180
	v_mul_f32_e32 v42, 0xbfb8aa3b, v42
	s_waitcnt vmcnt(18)
	v_lshlrev_b32_e32 v45, 16, v182
	v_exp_f32_e32 v42, v42
	v_mul_f32_e32 v45, 0xbfb8aa3b, v45
	v_exp_f32_e32 v45, v45
	s_waitcnt vmcnt(14)
	v_lshlrev_b32_e32 v47, 16, v204
	v_add_f32_e32 v42, 1.0, v42
	v_rcp_f32_e32 v56, v42
	v_add_f32_e32 v42, 1.0, v45
	v_lshlrev_b32_e32 v45, 16, v185
	v_mul_f32_e32 v45, 0xbfb8aa3b, v45
	v_exp_f32_e32 v45, v45
	v_mul_f32_e32 v47, 0xbfb8aa3b, v47
	v_exp_f32_e32 v47, v47
	v_rcp_f32_e32 v57, v42
	v_add_f32_e32 v42, 1.0, v45
	v_rcp_f32_e32 v58, v42
	v_add_f32_e32 v42, 1.0, v47
	v_rcp_f32_e32 v59, v42
	s_waitcnt vmcnt(12)
	v_lshlrev_b32_e32 v42, 16, v206
	v_mul_f32_e32 v42, 0xbfb8aa3b, v42
	v_lshlrev_b32_e32 v45, 16, v207
	v_exp_f32_e32 v42, v42
	v_mul_f32_e32 v45, 0xbfb8aa3b, v45
	v_exp_f32_e32 v45, v45
	v_pk_fma_f32 v[84:85], v[52:53], v[56:57], v[50:51]
	v_add_f32_e32 v42, 1.0, v42
	v_rcp_f32_e32 v56, v42
	v_add_f32_e32 v42, 1.0, v45
	v_lshlrev_b32_e32 v45, 16, v210
	v_mul_f32_e32 v45, 0xbfb8aa3b, v45
	v_lshlrev_b32_e32 v47, 16, v212
	v_exp_f32_e32 v45, v45
	v_mul_f32_e32 v47, 0xbfb8aa3b, v47
	v_exp_f32_e32 v47, v47
	v_rcp_f32_e32 v57, v42
	v_add_f32_e32 v42, 1.0, v45
	v_pk_fma_f32 v[86:87], v[52:53], v[58:59], v[50:51]
	v_rcp_f32_e32 v58, v42
	v_add_f32_e32 v42, 1.0, v47
	v_rcp_f32_e32 v59, v42
	s_waitcnt vmcnt(9)
	v_lshlrev_b32_e32 v42, 16, v214
	v_mul_f32_e32 v42, 0xbfb8aa3b, v42
	s_waitcnt vmcnt(7)
	v_lshlrev_b32_e32 v45, 16, v216
	v_exp_f32_e32 v42, v42
	v_mul_f32_e32 v45, 0xbfb8aa3b, v45
	v_exp_f32_e32 v45, v45
	v_pk_fma_f32 v[88:89], v[52:53], v[56:57], v[50:51]
	v_add_f32_e32 v42, 1.0, v42
	v_rcp_f32_e32 v56, v42
	v_add_f32_e32 v42, 1.0, v45
	s_waitcnt vmcnt(5)
	v_lshlrev_b32_e32 v45, 16, v218
	v_mul_f32_e32 v45, 0xbfb8aa3b, v45
	s_waitcnt vmcnt(3)
	v_lshlrev_b32_e32 v47, 16, v225
	v_exp_f32_e32 v45, v45
	v_mul_f32_e32 v47, 0xbfb8aa3b, v47
	v_exp_f32_e32 v47, v47
	v_rcp_f32_e32 v57, v42
	v_add_f32_e32 v42, 1.0, v45
	v_pk_fma_f32 v[90:91], v[52:53], v[58:59], v[50:51]
	v_rcp_f32_e32 v58, v42
	v_add_f32_e32 v42, 1.0, v47
	v_rcp_f32_e32 v59, v42
	s_waitcnt vmcnt(1)
	s_cmp_lt_i32 s43, 1
	s_cbranch_scc1 .Lhg_nopf
	s_add_i32 s36, s42, 1
	s_add_i32 s37, s43, -1
	s_and_b64 vcc, s[24:25], exec
	s_cselect_b32 s36, s36, s37
	s_lshl_b32 s36, s36, 6
	v_and_b32_e32 v236, 15, v200
	v_sub_u32_e32 v238, 0, v236
	v_bfe_u32 v239, v200, 4, 2
	v_cndmask_b32_e64 v236, v238, v236, s[24:25]
	v_add3_u32 v238, s36, v186, v236
	s_add_i32 s37, s30, 0x800
	v_mad_i64_i32 v[236:237], s[44:45], v238, s40, v[48:49]
	v_cmp_eq_u32_e32 vcc, 1, v239
	v_mov_b32_e32 v240, 0
	v_mov_b32_e32 v242, s37
	v_cndmask_b32_e32 v240, v240, v242, vcc
	v_cmp_eq_u32_e32 vcc, 2, v239
	v_mov_b32_e32 v242, 0x1800
	v_mov_b32_e32 v241, 0
	v_cndmask_b32_e32 v240, v240, v242, vcc
	v_lshl_add_u64 v[236:237], v[236:237], 0, v[240:241]
	global_load_ubyte v251, v[236:237], off
.Lhg_nopf:
	v_lshlrev_b32_e32 v42, 16, v227
	v_mul_f32_e32 v42, 0xbfb8aa3b, v42
	v_lshlrev_b32_e32 v45, 16, v219
	v_exp_f32_e32 v42, v42
	v_mul_f32_e32 v45, 0xbfb8aa3b, v45
	v_exp_f32_e32 v45, v45
	v_pk_mul_f32 v[82:83], v[84:85], v[84:85] op_sel:[0,1] op_sel_hi:[1,0]
	v_add_f32_e32 v42, 1.0, v42
	v_pk_fma_f32 v[92:93], v[52:53], v[56:57], v[50:51]
	v_rcp_f32_e32 v56, v42
	v_add_f32_e32 v42, 1.0, v45
	v_lshlrev_b32_e32 v45, 16, v221
	v_pk_mul_f32 v[72:73], v[82:83], v[86:87]
	v_mul_f32_e32 v45, 0xbfb8aa3b, v45
	v_lshlrev_b32_e32 v47, 16, v223
	v_pk_mul_f32 v[76:77], v[72:73], v[86:87] op_sel:[0,1] op_sel_hi:[1,0]
	v_exp_f32_e32 v45, v45
	v_mul_f32_e32 v47, 0xbfb8aa3b, v47
	v_pk_mul_f32 v[80:81], v[76:77], v[88:89]
	v_exp_f32_e32 v47, v47
	v_pk_mul_f32 v[78:79], v[80:81], v[88:89] op_sel:[0,1] op_sel_hi:[1,0]
	v_rcp_f32_e32 v57, v42
	v_pk_mul_f32 v[66:67], v[78:79], v[90:91]
	v_add_f32_e32 v42, 1.0, v45
	v_pk_mul_f32 v[74:75], v[66:67], v[90:91] op_sel:[0,1] op_sel_hi:[1,0]
	v_rcp_f32_e32 v98, v42
	v_pk_mul_f32 v[70:71], v[74:75], v[92:93]
	v_add_f32_e32 v42, 1.0, v47
	v_pk_mul_f32 v[68:69], v[70:71], v[92:93] op_sel:[0,1] op_sel_hi:[1,0]
	v_pk_fma_f32 v[94:95], v[52:53], v[58:59], v[50:51]
	v_rcp_f32_e32 v99, v42
	v_pk_mul_f32 v[58:59], v[68:69], v[94:95]
	v_pk_fma_f32 v[96:97], v[52:53], v[56:57], v[50:51]
	v_pk_mul_f32 v[60:61], v[58:59], v[94:95] op_sel:[0,1] op_sel_hi:[1,0]
	v_pk_fma_f32 v[98:99], v[52:53], v[98:99], v[50:51]
	v_pk_mul_f32 v[64:65], v[60:61], v[96:97]
	s_nop 0
	v_pk_mul_f32 v[62:63], v[64:65], v[96:97] op_sel:[0,1] op_sel_hi:[1,0]
	s_nop 0
	v_pk_mul_f32 v[56:57], v[62:63], v[98:99]
	s_nop 0
	v_mul_f32_e32 v45, v56, v99
	ds_write_b32 v135, v45
	ds_write_b128 v136, v[32:35] offset:53248
	ds_write_b128 v136, v[36:39] offset:53264
	s_waitcnt lgkmcnt(0)
	s_barrier
; #define LAS __attribute__((address_space(3)))
; __device__ __forceinline__ unsigned pk2(float lo, float hi) { const f32x2 v = {lo, hi}; return __builtin_bit_cast(unsigned, __builtin_convertvector(v, bf16x2_t)); }
; __device__ __forceinline__ unsigned f2bf(float f) { return pk2(f, 0.f) & 0xffffu; }
; __device__ __forceinline__ float frcp(float x) { return __builtin_amdgcn_rcpf(x); }
; __device__ __forceinline__ void hgrn_chain(LAS unsigned char* lds, int cid, bf16_t* P1, const float* hg_lb, bf16_t* Ob, int ldo, int ocbase, int ocdir) {
;     ...
;         { float pre = 1.0f, tot = 1.0f;
; #pragma unroll
;           for (int q4 = 0; q4 < 4; ++q4) { const float tq = totS[q4 * 128 + dcol]; if (q4 < qtr) pre *= tq; tot *= tq; }
;           const float etot = tot;
;           if (qtr == 0) lastS[dcol] = etot;
; #pragma unroll
;           for (int i = 0; i < 16; i += 2) { const float e0 = fmaxf(pre * gc[i], 1e-30f), e1 = fmaxf(pre * gc[i + 1], 1e-30f), n0 = frcp(e0), n1 = frcp(e1), l0 = etot * n0, l1 = etot * n1;
;               QE[(i0 + i) * HLD + dcol] = (bf16_t)f2bf(gq[i] * e0); QE[(i0 + i + 1) * HLD + dcol] = (bf16_t)f2bf(gq[i + 1] * e1);
;               KE[(i0 + i) * HLD + dcol] = (bf16_t)f2bf(gk[i] * n0); KE[(i0 + i + 1) * HLD + dcol] = (bf16_t)f2bf(gk[i + 1] * n1);
;               *(LAS unsigned*)(KLT + dcol * HLS + i0 + i) = pk2(gk[i] * l0, gk[i + 1] * l1); } }
	ds_read2st64_b32 v[102:103], v137 offset1:2
	ds_read2st64_b32 v[100:101], v137 offset0:4 offset1:6
	s_waitcnt lgkmcnt(1)
	v_mul_f32_e32 v42, v102, v103
	s_waitcnt lgkmcnt(0)
	v_mul_f32_e32 v42, v42, v100
	v_mul_f32_e32 v42, v42, v101
	s_and_saveexec_b64 s[36:37], s[0:1]
	ds_write_b32 v143, v42
	s_or_b64 exec, exec, s[36:37]
	v_cndmask_b32_e64 v67, v102, 1.0, s[0:1]
	v_mul_f32_e32 v73, v67, v103
	v_cndmask_b32_e64 v67, v67, v73, s[2:3]
	v_mul_f32_e32 v73, v100, v67
	v_cndmask_b32_e64 v67, v67, v73, s[4:5]
	v_mul_f32_e32 v73, v101, v67
	v_cndmask_b32_e64 v100, v67, v73, s[6:7]
	v_mul_f32_e32 v67, v84, v100
	v_lshlrev_b32_e32 v47, 16, v179
	v_max_f32_e32 v67, 0xda24260, v67
	v_mul_f32_e32 v73, v82, v100
	v_rcp_f32_e32 v82, v67
	v_mul_f32_e32 v47, v67, v47
	v_lshlrev_b32_e32 v57, 16, v181
	v_max_f32_e32 v73, 0xda24260, v73
	v_cvt_pk_bf16_f32 v47, v47, s0
	v_rcp_f32_e32 v83, v73
	ds_write_b16 v144, v47
	v_mul_f32_e32 v47, v73, v57
	v_pk_add_f32 v[230:231], v[84:85], 1.0 op_sel_hi:[1,0] neg_lo:[1,0] neg_hi:[1,0]
	v_cvt_pk_bf16_f32 v47, v47, s0
	ds_write_b16 v144, v47 offset:272
	v_mul_f32_e32 v47, v230, v82
	v_cvt_pk_bf16_f32 v47, v47, s0
	ds_write_b16 v144, v47 offset:17408
	v_mul_f32_e32 v47, v231, v83
	v_cvt_pk_bf16_f32 v47, v47, s0
	ds_write_b16 v144, v47 offset:17680
	v_mul_f32_e32 v47, v72, v100
	v_lshlrev_b32_e32 v59, 16, v183
	v_max_f32_e32 v47, 0xda24260, v47
	v_mul_f32_e32 v57, v76, v100
	v_rcp_f32_e32 v72, v47
	v_mul_f32_e32 v47, v47, v59
	v_lshlrev_b32_e32 v61, 16, v203
	v_max_f32_e32 v57, 0xda24260, v57
	v_cvt_pk_bf16_f32 v47, v47, s0
	v_rcp_f32_e32 v73, v57
	ds_write_b16 v144, v47 offset:544
	v_mul_f32_e32 v47, v57, v61
	v_pk_add_f32 v[86:87], v[86:87], 1.0 op_sel_hi:[1,0] neg_lo:[1,0] neg_hi:[1,0]
	v_cvt_pk_bf16_f32 v47, v47, s0
	ds_write_b16 v144, v47 offset:816
	v_mul_f32_e32 v47, v86, v72
	v_cvt_pk_bf16_f32 v47, v47, s0
	ds_write_b16 v144, v47 offset:17952
	v_mul_f32_e32 v47, v87, v73
	v_cvt_pk_bf16_f32 v47, v47, s0
	v_pk_mul_f32 v[82:83], v[42:43], v[82:83] op_sel_hi:[0,1]
	ds_write_b16 v144, v47 offset:18224
	v_pk_mul_f32 v[72:73], v[42:43], v[72:73] op_sel_hi:[0,1]
	v_mul_f32_e32 v47, v80, v100
	v_lshlrev_b32_e32 v63, 16, v205
	v_pk_mul_f32 v[82:83], v[230:231], v[82:83]
	v_pk_mul_f32 v[72:73], v[86:87], v[72:73]
	v_max_f32_e32 v47, 0xda24260, v47
	v_cvt_pk_bf16_f32 v82, v82, v83
	v_cvt_pk_bf16_f32 v83, v72, v73
	v_mul_f32_e32 v57, v78, v100
	v_rcp_f32_e32 v72, v47
	v_mul_f32_e32 v47, v47, v63
	v_lshlrev_b32_e32 v65, 16, v208
	v_max_f32_e32 v57, 0xda24260, v57
	v_cvt_pk_bf16_f32 v47, v47, s0
	v_rcp_f32_e32 v73, v57
	ds_write_b16 v144, v47 offset:1088
	v_mul_f32_e32 v47, v57, v65
	v_pk_add_f32 v[88:89], v[88:89], 1.0 op_sel_hi:[1,0] neg_lo:[1,0] neg_hi:[1,0]
	v_cvt_pk_bf16_f32 v47, v47, s0
	ds_write_b16 v144, v47 offset:1360
	v_mul_f32_e32 v47, v88, v72
	v_cvt_pk_bf16_f32 v47, v47, s0
	ds_write_b16 v144, v47 offset:18496
	v_mul_f32_e32 v47, v89, v73
	v_cvt_pk_bf16_f32 v47, v47, s0
	ds_write_b16 v144, v47 offset:18768
	v_mul_f32_e32 v47, v66, v100
	v_lshlrev_b32_e32 v69, 16, v209
	v_max_f32_e32 v47, 0xda24260, v47
	v_mul_f32_e32 v57, v74, v100
	v_rcp_f32_e32 v66, v47
	v_mul_f32_e32 v47, v47, v69
	v_lshlrev_b32_e32 v71, 16, v211
	v_max_f32_e32 v57, 0xda24260, v57
	v_cvt_pk_bf16_f32 v47, v47, s0
	v_rcp_f32_e32 v67, v57
	ds_write_b16 v144, v47 offset:1632
	v_mul_f32_e32 v47, v57, v71
	v_pk_add_f32 v[90:91], v[90:91], 1.0 op_sel_hi:[1,0] neg_lo:[1,0] neg_hi:[1,0]
	v_cvt_pk_bf16_f32 v47, v47, s0
	ds_write_b16 v144, v47 offset:1904
	v_mul_f32_e32 v47, v90, v66
	v_cvt_pk_bf16_f32 v47, v47, s0
	ds_write_b16 v144, v47 offset:19040
	v_mul_f32_e32 v47, v91, v67
	v_cvt_pk_bf16_f32 v47, v47, s0
	ds_write_b16 v144, v47 offset:19312
	v_pk_mul_f32 v[66:67], v[42:43], v[66:67] op_sel_hi:[0,1]
	v_mul_f32_e32 v47, v70, v100
	v_lshlrev_b32_e32 v75, 16, v213
	v_pk_mul_f32 v[66:67], v[90:91], v[66:67]
	v_max_f32_e32 v47, 0xda24260, v47
	v_cvt_pk_bf16_f32 v85, v66, v67
	v_mul_f32_e32 v57, v68, v100
	v_rcp_f32_e32 v66, v47
	v_mul_f32_e32 v47, v47, v75
	v_lshlrev_b32_e32 v77, 16, v215
	v_max_f32_e32 v57, 0xda24260, v57
	v_cvt_pk_bf16_f32 v47, v47, s0
	v_rcp_f32_e32 v67, v57
	ds_write_b16 v144, v47 offset:2176
	v_mul_f32_e32 v47, v57, v77
	v_pk_add_f32 v[92:93], v[92:93], 1.0 op_sel_hi:[1,0] neg_lo:[1,0] neg_hi:[1,0]
	v_cvt_pk_bf16_f32 v47, v47, s0
	ds_write_b16 v144, v47 offset:2448
	v_mul_f32_e32 v47, v92, v66
	v_cvt_pk_bf16_f32 v47, v47, s0
	ds_write_b16 v144, v47 offset:19584
	v_mul_f32_e32 v47, v93, v67
	v_cvt_pk_bf16_f32 v47, v47, s0
	ds_write_b16 v144, v47 offset:19856
	v_mul_f32_e32 v47, v58, v100
	v_lshlrev_b32_e32 v79, 16, v217
	v_max_f32_e32 v47, 0xda24260, v47
	v_mul_f32_e32 v57, v60, v100
	v_rcp_f32_e32 v58, v47
	v_mul_f32_e32 v47, v47, v79
	v_lshlrev_b32_e32 v81, 16, v224
	v_max_f32_e32 v57, 0xda24260, v57
	v_cvt_pk_bf16_f32 v47, v47, s0
	v_rcp_f32_e32 v59, v57
	ds_write_b16 v144, v47 offset:2720
	v_mul_f32_e32 v47, v57, v81
	v_pk_add_f32 v[94:95], v[94:95], 1.0 op_sel_hi:[1,0] neg_lo:[1,0] neg_hi:[1,0]
	v_cvt_pk_bf16_f32 v47, v47, s0
	ds_write_b16 v144, v47 offset:2992
	v_mul_f32_e32 v47, v94, v58
	v_cvt_pk_bf16_f32 v47, v47, s0
	ds_write_b16 v144, v47 offset:20128
	v_mul_f32_e32 v47, v95, v59
	v_cvt_pk_bf16_f32 v47, v47, s0
	v_pk_mul_f32 v[66:67], v[42:43], v[66:67] op_sel_hi:[0,1]
	ds_write_b16 v144, v47 offset:20400
	v_pk_mul_f32 v[58:59], v[42:43], v[58:59] op_sel_hi:[0,1]
	v_mul_f32_e32 v47, v64, v100
	v_lshlrev_b32_e32 v229, 16, v226
	v_pk_mul_f32 v[66:67], v[92:93], v[66:67]
	v_pk_mul_f32 v[58:59], v[94:95], v[58:59]
	v_max_f32_e32 v47, 0xda24260, v47
	v_cvt_pk_bf16_f32 v66, v66, v67
	v_cvt_pk_bf16_f32 v67, v58, v59
	v_mul_f32_e32 v57, v62, v100
	v_rcp_f32_e32 v58, v47
	v_mul_f32_e32 v47, v47, v229
	s_waitcnt vmcnt(1)
; #define LAS __attribute__((address_space(3)))
; __device__ __forceinline__ unsigned pk2(float lo, float hi) { const f32x2 v = {lo, hi}; return __builtin_bit_cast(unsigned, __builtin_convertvector(v, bf16x2_t)); }
; __device__ __forceinline__ unsigned f2bf(float f) { return pk2(f, 0.f) & 0xffffu; }
; __device__ __forceinline__ float frcp(float x) { return __builtin_amdgcn_rcpf(x); }
; #define HG_ISSUE(t0n) do { _Pragma("unroll") for (int i = 0; i < 16; ++i) { const int tk = (t0n) + (dir ? 63 - (i0 + i) : (i0 + i)); const bf16_t* pr = Pb + (size_t)tk * HGP + h * 128 + dcol; \
;         rq[i] = pr[0]; rf[i] = pr[1024 * (1 + dir)]; rv[i] = pr[3072]; } } while (0)
; __device__ __forceinline__ void hgrn_chain(LAS unsigned char* lds, int cid, bf16_t* P1, const float* hg_lb, bf16_t* Ob, int ldo, int ocbase, int ocdir) {
;     ...
; #pragma unroll
;           for (int i = 0; i < 16; i += 2) { const float e0 = fmaxf(pre * gc[i], 1e-30f), e1 = fmaxf(pre * gc[i + 1], 1e-30f), n0 = frcp(e0), n1 = frcp(e1), l0 = etot * n0, l1 = etot * n1;
;               QE[(i0 + i) * HLD + dcol] = (bf16_t)f2bf(gq[i] * e0); QE[(i0 + i + 1) * HLD + dcol] = (bf16_t)f2bf(gq[i + 1] * e1);
;               KE[(i0 + i) * HLD + dcol] = (bf16_t)f2bf(gk[i] * n0); KE[(i0 + i + 1) * HLD + dcol] = (bf16_t)f2bf(gk[i + 1] * n1);
;               *(LAS unsigned*)(KLT + dcol * HLS + i0 + i) = pk2(gk[i] * l0, gk[i + 1] * l1); } }
;         if (cc + 1 < 64) HG_ISSUE((dir ? 62 - cc : cc + 1) * 64);
	v_lshlrev_b32_e32 v232, 16, v228
	v_max_f32_e32 v57, 0xda24260, v57
	v_cvt_pk_bf16_f32 v47, v47, s0
	v_rcp_f32_e32 v59, v57
	ds_write_b16 v144, v47 offset:3264
	v_mul_f32_e32 v47, v57, v232
	v_pk_add_f32 v[96:97], v[96:97], 1.0 op_sel_hi:[1,0] neg_lo:[1,0] neg_hi:[1,0]
	v_cvt_pk_bf16_f32 v47, v47, s0
	ds_write_b16 v144, v47 offset:3536
	v_mul_f32_e32 v47, v96, v58
	v_cvt_pk_bf16_f32 v47, v47, s0
	ds_write_b16 v144, v47 offset:20672
	v_mul_f32_e32 v47, v97, v59
	v_cvt_pk_bf16_f32 v47, v47, s0
	ds_write_b16 v144, v47 offset:20944
	v_mul_f32_e32 v47, v56, v100
	v_max_f32_e32 v47, 0xda24260, v47
	v_mul_f32_e32 v45, v45, v100
	v_rcp_f32_e32 v56, v47
	v_lshlrev_b32_e32 v234, 16, v222
	v_max_f32_e32 v45, 0xda24260, v45
	v_rcp_f32_e32 v57, v45
	v_mul_f32_e32 v45, v45, v234
	v_pk_add_f32 v[98:99], v[98:99], 1.0 op_sel_hi:[1,0] neg_lo:[1,0] neg_hi:[1,0]
	v_cvt_pk_bf16_f32 v45, v45, s0
	ds_write_b16 v144, v45 offset:4080
	v_mul_f32_e32 v45, v98, v56
	v_cvt_pk_bf16_f32 v45, v45, s0
	v_lshlrev_b32_e32 v233, 16, v220
	v_pk_mul_f32 v[72:73], v[42:43], v[72:73] op_sel_hi:[0,1]
	v_pk_mul_f32 v[58:59], v[42:43], v[58:59] op_sel_hi:[0,1]
	ds_write_b16 v144, v45 offset:21216
	v_mul_f32_e32 v45, v99, v57
	v_pk_mul_f32 v[56:57], v[42:43], v[56:57] op_sel_hi:[0,1]
	v_pk_mul_f32 v[72:73], v[88:89], v[72:73]
	v_pk_mul_f32 v[58:59], v[96:97], v[58:59]
	v_mul_f32_e32 v47, v47, v233
	v_pk_mul_f32 v[56:57], v[98:99], v[56:57]
	v_cvt_pk_bf16_f32 v84, v72, v73
	v_cvt_pk_bf16_f32 v68, v58, v59
	v_cvt_pk_bf16_f32 v47, v47, s0
	v_cvt_pk_bf16_f32 v45, v45, s0
	v_cvt_pk_bf16_f32 v69, v56, v57
	s_cmp_eq_u32 s43, -1
	ds_write_b128 v136, v[82:85] offset:34816
	ds_write_b16 v144, v47 offset:3808
	ds_write_b16 v144, v45 offset:21488
	ds_write_b128 v136, v[66:69] offset:34832
	s_cbranch_scc1 .LBB0_1715
; #define HG_ISSUE(t0n) do { _Pragma("unroll") for (int i = 0; i < 16; ++i) { const int tk = (t0n) + (dir ? 63 - (i0 + i) : (i0 + i)); const bf16_t* pr = Pb + (size_t)tk * HGP + h * 128 + dcol; \
;         rq[i] = pr[0]; rf[i] = pr[1024 * (1 + dir)]; rv[i] = pr[3072]; } } while (0)
; __device__ __forceinline__ void hgrn_chain(LAS unsigned char* lds, int cid, bf16_t* P1, const float* hg_lb, bf16_t* Ob, int ldo, int ocbase, int ocdir) {
;     ...
;         if (cc + 1 < 64) HG_ISSUE((dir ? 62 - cc : cc + 1) * 64);
	s_and_b64 s[36:37], s[24:25], exec
	s_cselect_b32 s36, s42, s43
	s_lshl_b32 s36, s36, 6
	v_add_u32_e32 v32, s36, v186
	v_mad_i64_i32 v[32:33], s[44:45], v32, s40, v[48:49]
	v_add_co_u32_e32 v36, vcc, 0x1000, v32
	v_add_u32_e32 v38, s36, v187
	s_nop 0
	v_addc_co_u32_e32 v37, vcc, 0, v33, vcc
	v_mad_i64_i32 v[38:39], s[44:45], v38, s40, v[48:49]
	v_add_co_u32_e32 v58, vcc, 0x1000, v38
	v_add_u32_e32 v42, s36, v188
	v_lshl_add_u64 v[34:35], v[32:33], 0, s[30:31]
	v_addc_co_u32_e32 v59, vcc, 0, v39, vcc
	v_mad_i64_i32 v[60:61], s[44:45], v42, s40, v[48:49]
	v_lshl_add_u64 v[56:57], v[38:39], 0, s[30:31]
	v_lshl_add_u64 v[62:63], v[60:61], 0, s[30:31]
	global_load_ushort v179, v[32:33], off
	global_load_ushort v180, v[34:35], off offset:2048
	global_load_ushort v235, v[36:37], off offset:2048
	global_load_ushort v181, v[38:39], off
	global_load_ushort v182, v[56:57], off offset:2048
	global_load_ushort v236, v[58:59], off offset:2048
	global_load_ushort v183, v[60:61], off
	global_load_ushort v185, v[62:63], off offset:2048
	v_add_co_u32_e32 v32, vcc, 0x1000, v60
	v_add_u32_e32 v34, s36, v189
	s_nop 0
	v_addc_co_u32_e32 v33, vcc, 0, v61, vcc
	v_mad_i64_i32 v[34:35], s[44:45], v34, s40, v[48:49]
	v_add_co_u32_e32 v38, vcc, 0x1000, v34
	v_add_u32_e32 v47, s36, v190
	s_nop 0
	v_addc_co_u32_e32 v39, vcc, 0, v35, vcc
	v_mad_i64_i32 v[56:57], s[44:45], v47, s40, v[48:49]
	v_add_co_u32_e32 v60, vcc, 0x1000, v56
	v_add_u32_e32 v47, s36, v191
	v_lshl_add_u64 v[36:37], v[34:35], 0, s[30:31]
	v_addc_co_u32_e32 v61, vcc, 0, v57, vcc
	v_mad_i64_i32 v[62:63], s[44:45], v47, s40, v[48:49]
	v_lshl_add_u64 v[58:59], v[56:57], 0, s[30:31]
	global_load_ushort v237, v[32:33], off offset:2048
	global_load_ushort v203, v[34:35], off
	global_load_ushort v204, v[36:37], off offset:2048
	global_load_ushort v238, v[38:39], off offset:2048
	global_load_ushort v205, v[56:57], off
	global_load_ushort v206, v[58:59], off offset:2048
	global_load_ushort v239, v[60:61], off offset:2048
	global_load_ushort v208, v[62:63], off
	v_add_co_u32_e32 v34, vcc, 0x1000, v62
	v_add_u32_e32 v36, s36, v192
	s_nop 0
	v_addc_co_u32_e32 v35, vcc, 0, v63, vcc
	v_mad_i64_i32 v[36:37], s[44:45], v36, s40, v[48:49]
	v_add_co_u32_e32 v56, vcc, 0x1000, v36
	v_add_u32_e32 v58, s36, v193
	s_nop 0
	v_addc_co_u32_e32 v57, vcc, 0, v37, vcc
	v_mad_i64_i32 v[58:59], s[44:45], v58, s40, v[48:49]
	v_lshl_add_u64 v[32:33], v[62:63], 0, s[30:31]
	v_add_co_u32_e32 v62, vcc, 0x1000, v58
	v_lshl_add_u64 v[38:39], v[36:37], 0, s[30:31]
	v_lshl_add_u64 v[60:61], v[58:59], 0, s[30:31]
	v_addc_co_u32_e32 v63, vcc, 0, v59, vcc
	global_load_ushort v207, v[32:33], off offset:2048
	global_load_ushort v240, v[34:35], off offset:2048
	global_load_ushort v209, v[36:37], off
	global_load_ushort v210, v[38:39], off offset:2048
	global_load_ushort v241, v[56:57], off offset:2048
	global_load_ushort v211, v[58:59], off
	global_load_ushort v212, v[60:61], off offset:2048
	global_load_ushort v242, v[62:63], off offset:2048
	v_add_u32_e32 v32, s36, v194
	v_mad_i64_i32 v[32:33], s[44:45], v32, s40, v[48:49]
	v_add_co_u32_e32 v36, vcc, 0x1000, v32
	v_add_u32_e32 v38, s36, v195
	s_nop 0
	v_addc_co_u32_e32 v37, vcc, 0, v33, vcc
	v_mad_i64_i32 v[38:39], s[44:45], v38, s40, v[48:49]
	v_add_co_u32_e32 v58, vcc, 0x1000, v38
	v_add_u32_e32 v60, s36, v196
	v_lshl_add_u64 v[34:35], v[32:33], 0, s[30:31]
	v_addc_co_u32_e32 v59, vcc, 0, v39, vcc
	v_mad_i64_i32 v[60:61], s[44:45], v60, s40, v[48:49]
	v_lshl_add_u64 v[56:57], v[38:39], 0, s[30:31]
	v_lshl_add_u64 v[62:63], v[60:61], 0, s[30:31]
	global_load_ushort v213, v[32:33], off
	global_load_ushort v214, v[34:35], off offset:2048
	global_load_ushort v243, v[36:37], off offset:2048
	global_load_ushort v215, v[38:39], off
	global_load_ushort v216, v[56:57], off offset:2048
	global_load_ushort v244, v[58:59], off offset:2048
	global_load_ushort v217, v[60:61], off
	global_load_ushort v218, v[62:63], off offset:2048
	v_add_co_u32_e32 v32, vcc, 0x1000, v60
	v_add_u32_e32 v34, s36, v197
	s_nop 0
	v_addc_co_u32_e32 v33, vcc, 0, v61, vcc
	v_mad_i64_i32 v[34:35], s[44:45], v34, s40, v[48:49]
	v_add_co_u32_e32 v38, vcc, 0x1000, v34
	v_add_u32_e32 v56, s36, v198
	s_nop 0
	v_addc_co_u32_e32 v39, vcc, 0, v35, vcc
	v_mad_i64_i32 v[56:57], s[44:45], v56, s40, v[48:49]
	v_add_co_u32_e32 v60, vcc, 0x1000, v56
	v_add_u32_e32 v62, s36, v199
	s_nop 0
	v_addc_co_u32_e32 v61, vcc, 0, v57, vcc
	v_mad_i64_i32 v[62:63], s[44:45], v62, s40, v[48:49]
	v_add_co_u32_e32 v66, vcc, 0x1000, v62
	v_add_u32_e32 v68, s36, v201
	s_nop 0
	v_addc_co_u32_e32 v67, vcc, 0, v63, vcc
	v_mad_i64_i32 v[68:69], s[44:45], v68, s40, v[48:49]
	v_add_co_u32_e32 v72, vcc, 0x1000, v68
	v_add_u32_e32 v74, s36, v202
	s_nop 0
	v_addc_co_u32_e32 v73, vcc, 0, v69, vcc
	v_mad_i64_i32 v[74:75], s[36:37], v74, s40, v[48:49]
	v_lshl_add_u64 v[36:37], v[34:35], 0, s[30:31]
	v_lshl_add_u64 v[64:65], v[62:63], 0, s[30:31]
	v_add_co_u32_e32 v78, vcc, 0x1000, v74
	v_lshl_add_u64 v[58:59], v[56:57], 0, s[30:31]
	v_lshl_add_u64 v[70:71], v[68:69], 0, s[30:31]
	v_lshl_add_u64 v[76:77], v[74:75], 0, s[30:31]
	v_addc_co_u32_e32 v79, vcc, 0, v75, vcc
	global_load_ushort v219, v[64:65], off offset:2048
	s_nop 0
	global_load_ushort v250, v[66:67], off offset:2048
	global_load_ushort v220, v[68:69], off
	global_load_ushort v221, v[70:71], off offset:2048
	global_load_ushort v245, v[72:73], off offset:2048
	global_load_ushort v222, v[74:75], off
	global_load_ushort v223, v[76:77], off offset:2048
	global_load_ushort v246, v[78:79], off offset:2048
	global_load_ushort v247, v[32:33], off offset:2048
	global_load_ushort v224, v[34:35], off
	global_load_ushort v225, v[36:37], off offset:2048
	s_nop 0
	global_load_ushort v248, v[38:39], off offset:2048
	global_load_ushort v226, v[56:57], off
	s_nop 0
	global_load_ushort v249, v[60:61], off offset:2048
	global_load_ushort v227, v[58:59], off offset:2048
	global_load_ushort v228, v[62:63], off
	s_branch .LBB0_1715
